# conformer conv: the 31 depthwise weight pairs of a thread loaded once per phase into dedicated registers instead of once per item behind the half-block barrier
# speedup vs baseline: 1.0011x; 1.0004x over previous
; DI int vb_id() { return (int)blockIdx.x + half_id() * (int)gridDim.x; }
; DI int vb_n() { return (int)gridDim.x * 2; }
; DI void conv_item(const Params& p, int item, char* smem) {
;     ...
;   for (int pass = 0; pass < 2; ++pass) {
;     float w[31];
; #pragma unroll
;     for (int k = 0; k < 31; ++k) w[k] = p.w_dw[k * 512 + c0 + pass];
; DI void phase_mix(const Params& p, char* smem) {
;     ...
;     for (int it = vb_id(); it < 1024; it += vb_n(), ++rnd) {
;       const int item = (rnd & 1) ? (1023 - (it - rnd * vb_n())) - ((rnd - 1) * vb_n()) : it;
;       if (item >= 0 && item < 1024) attn_item(p, item, smem);
;     }
;   }
;   for (int it = vb_id(); it < 1024; it += vb_n()) conv_item(p, it, smem);
.LBB0_658:
	v_readfirstlane_b32 s0, v211
	s_lshr_b32 s0, s0, 8
	v_readlane_b32 s60, v253, 54
	v_readlane_b32 s64, v253, 34
	s_mul_i32 s0, s0, s60
	v_readlane_b32 s55, v253, 56
	v_readlane_b32 s68, v253, 38
	v_readlane_b32 s69, v253, 39
	s_add_i32 s9, s0, s55
	v_readlane_b32 s66, v253, 36
	v_readlane_b32 s67, v253, 37
	v_readlane_b32 s62, v253, 52
	v_readlane_b32 s68, v253, 32
	v_readlane_b32 s61, v253, 55
	s_cmpk_gt_i32 s9, 0x3ff
	v_readlane_b32 s65, v253, 35
	v_readlane_b32 s74, v253, 44
	v_readlane_b32 s75, v253, 45
	v_readlane_b32 s76, v253, 46
	v_readlane_b32 s77, v253, 47
	v_readlane_b32 s78, v253, 48
	v_readlane_b32 s79, v253, 49
	v_readlane_b32 s63, v253, 53
	v_readlane_b32 s66, v253, 51
	v_readlane_b32 s69, v253, 33
	v_readlane_b32 s67, v253, 50
	v_readlane_b32 s70, v253, 40
	v_readlane_b32 s71, v253, 41
	v_readlane_b32 s72, v253, 42
	v_readlane_b32 s73, v253, 43
	s_cbranch_scc1 .LBB0_752
	s_add_u32 s2, s78, 0x9c80200
	s_addc_u32 s3, s79, 0
	s_add_u32 s6, s76, 0x1000000
	v_cmp_eq_u32_e64 s[4:5], 0, v213
	s_addc_u32 s7, s77, 0
	v_mov_b32_e32 v1, 0
	s_waitcnt vmcnt(0)
	v_mbcnt_hi_u32_b32 v156, -1, v212
	s_movk_i32 s11, 0x820
	s_mov_b32 s8, 0x3b000000
	s_mov_b32 s10, 0x358637bd
	s_mov_b32 s20, 0x800000
	s_movk_i32 s21, 0x7fff
	v_readlane_b32 s98, v253, 20
	v_readlane_b32 s99, v253, 21
	v_lshlrev_b32_e32 v242, 3, v210
	s_nop 4
	global_load_dwordx2 v[176:177], v242, s[98:99]
	global_load_dwordx2 v[178:179], v242, s[98:99] offset:2048
	v_add_u32_e32 v243, 0x1000, v242
	global_load_dwordx2 v[180:181], v243, s[98:99]
	global_load_dwordx2 v[182:183], v243, s[98:99] offset:2048
	v_add_u32_e32 v243, 0x2000, v242
	global_load_dwordx2 v[184:185], v243, s[98:99]
	global_load_dwordx2 v[186:187], v243, s[98:99] offset:2048
	v_add_u32_e32 v243, 0x3000, v242
	global_load_dwordx2 v[188:189], v243, s[98:99]
	global_load_dwordx2 v[190:191], v243, s[98:99] offset:2048
	v_add_u32_e32 v243, 0x4000, v242
	global_load_dwordx2 v[192:193], v243, s[98:99]
	global_load_dwordx2 v[194:195], v243, s[98:99] offset:2048
	v_add_u32_e32 v243, 0x5000, v242
	global_load_dwordx2 v[196:197], v243, s[98:99]
	global_load_dwordx2 v[198:199], v243, s[98:99] offset:2048
	v_add_u32_e32 v243, 0x6000, v242
	global_load_dwordx2 v[200:201], v243, s[98:99]
	global_load_dwordx2 v[202:203], v243, s[98:99] offset:2048
	v_add_u32_e32 v243, 0x7000, v242
	global_load_dwordx2 v[204:205], v243, s[98:99]
	global_load_dwordx2 v[206:207], v243, s[98:99] offset:2048
	v_add_u32_e32 v243, 0x8000, v242
	global_load_dwordx2 v[208:209], v243, s[98:99]
	global_load_dwordx2 v[214:215], v243, s[98:99] offset:2048
	v_add_u32_e32 v243, 0x9000, v242
	global_load_dwordx2 v[216:217], v243, s[98:99]
	global_load_dwordx2 v[218:219], v243, s[98:99] offset:2048
	v_add_u32_e32 v243, 0xa000, v242
	global_load_dwordx2 v[220:221], v243, s[98:99]
	global_load_dwordx2 v[222:223], v243, s[98:99] offset:2048
	v_add_u32_e32 v243, 0xb000, v242
	global_load_dwordx2 v[224:225], v243, s[98:99]
	global_load_dwordx2 v[226:227], v243, s[98:99] offset:2048
	v_add_u32_e32 v243, 0xc000, v242
	global_load_dwordx2 v[228:229], v243, s[98:99]
	global_load_dwordx2 v[230:231], v243, s[98:99] offset:2048
	v_add_u32_e32 v243, 0xd000, v242
	global_load_dwordx2 v[232:233], v243, s[98:99]
	global_load_dwordx2 v[234:235], v243, s[98:99] offset:2048
	v_add_u32_e32 v243, 0xe000, v242
	global_load_dwordx2 v[236:237], v243, s[98:99]
	global_load_dwordx2 v[238:239], v243, s[98:99] offset:2048
	v_add_u32_e32 v243, 0xf000, v242
	global_load_dwordx2 v[240:241], v243, s[98:99]
	s_branch .LBB0_661

; DI void hsync() { hsync_impl(false); }
; DI void conv_item(const Params& p, int item, char* smem) {
;     ...
;   const int b = item >> 8, t0 = (item & 255) * 16;
;   const int c0 = tid * 2;
;   const float2 bias = *(const float2*)(p.b_dw + c0);
;   unsigned rowv[46];
; #pragma unroll
;   for (int r = 0; r < 46; ++r) {
;     int tt = t0 - 30 + r;
;     rowv[r] = 0u;
;     if (tt >= 0) rowv[r] = *(const unsigned*)(GLU + ((size_t)(b * 4096 + tt)) * 512 + c0);
;   }
;   hsync();
; #pragma unroll
;   for (int pass = 0; pass < 2; ++pass) {
;     float w[31];
; #pragma unroll
;     for (int k = 0; k < 31; ++k) w[k] = p.w_dw[k * 512 + c0 + pass];
.LBB0_734:
	s_or_b64 exec, exec, s[0:1]
	v_readlane_b32 s36, v253, 16
	v_add_u32_e32 v6, 0x400, v4
	v_readlane_b32 s40, v253, 20
	v_readlane_b32 s41, v253, 21
	v_ashrrev_i32_e32 v7, 31, v6
	s_waitcnt vmcnt(0) lgkmcnt(0)
	s_waitcnt vmcnt(16)
	v_lshlrev_b32_e32 v174, 16, v25
	v_lshl_add_u64 v[12:13], v[6:7], 2, s[40:41]
	v_add_u32_e32 v6, 0x600, v4
	v_ashrrev_i32_e32 v7, 31, v6
	v_lshl_add_u64 v[14:15], v[6:7], 2, s[40:41]
	v_add_u32_e32 v6, 0x800, v4
	v_ashrrev_i32_e32 v7, 31, v6
	v_lshl_add_u64 v[16:17], v[6:7], 2, s[40:41]
	v_add_u32_e32 v6, 0xa00, v4
	v_ashrrev_i32_e32 v7, 31, v6
	v_lshl_add_u64 v[18:19], v[6:7], 2, s[40:41]
	v_add_u32_e32 v6, 0xc00, v4
	v_ashrrev_i32_e32 v7, 31, v6
	v_lshl_add_u64 v[20:21], v[6:7], 2, s[40:41]
	v_add_u32_e32 v6, 0xe00, v4
	v_ashrrev_i32_e32 v7, 31, v6
	v_lshl_add_u64 v[22:23], v[6:7], 2, s[40:41]
	v_add_u32_e32 v6, 0x1000, v4
	v_ashrrev_i32_e32 v7, 31, v6
	v_lshl_add_u64 v[30:31], v[6:7], 2, s[40:41]
	v_add_u32_e32 v6, 0x1200, v4
	v_ashrrev_i32_e32 v7, 31, v6
	v_lshl_add_u64 v[32:33], v[6:7], 2, s[40:41]
	v_add_u32_e32 v6, 0x1400, v4
	v_ashrrev_i32_e32 v7, 31, v6
	v_lshl_add_u64 v[34:35], v[6:7], 2, s[40:41]
	v_add_u32_e32 v6, 0x1600, v4
	v_ashrrev_i32_e32 v7, 31, v6
	v_lshl_add_u64 v[36:37], v[6:7], 2, s[40:41]
	v_add_u32_e32 v6, 0x1800, v4
	v_ashrrev_i32_e32 v7, 31, v6
	v_lshl_add_u64 v[38:39], v[6:7], 2, s[40:41]
	v_add_u32_e32 v6, 0x1a00, v4
	v_ashrrev_i32_e32 v7, 31, v6
	v_lshl_add_u64 v[40:41], v[6:7], 2, s[40:41]
	v_add_u32_e32 v6, 0x1c00, v4
	v_ashrrev_i32_e32 v7, 31, v6
	v_lshl_add_u64 v[42:43], v[6:7], 2, s[40:41]
	v_add_u32_e32 v6, 0x1e00, v4
	v_ashrrev_i32_e32 v7, 31, v6
	v_lshl_add_u64 v[44:45], v[6:7], 2, s[40:41]
	v_add_u32_e32 v6, 0x2000, v4
	v_ashrrev_i32_e32 v7, 31, v6
	v_lshl_add_u64 v[46:47], v[6:7], 2, s[40:41]
	v_add_u32_e32 v6, 0x2200, v4
	v_ashrrev_i32_e32 v7, 31, v6
	v_lshl_add_u64 v[50:51], v[6:7], 2, s[40:41]
	v_add_u32_e32 v6, 0x2400, v4
	v_ashrrev_i32_e32 v7, 31, v6
	v_lshl_add_u64 v[52:53], v[6:7], 2, s[40:41]
	v_add_u32_e32 v6, 0x2600, v4
	v_ashrrev_i32_e32 v7, 31, v6
	v_lshl_add_u64 v[76:77], v[6:7], 2, s[40:41]
	v_add_u32_e32 v6, 0x2800, v4
	v_ashrrev_i32_e32 v7, 31, v6
	v_lshl_add_u64 v[80:81], v[6:7], 2, s[40:41]
	v_add_u32_e32 v6, 0x2a00, v4
	v_ashrrev_i32_e32 v7, 31, v6
	v_lshl_add_u64 v[82:83], v[6:7], 2, s[40:41]
	v_add_u32_e32 v6, 0x2c00, v4
	v_ashrrev_i32_e32 v7, 31, v6
	v_lshl_add_u64 v[84:85], v[6:7], 2, s[40:41]
	v_add_u32_e32 v6, 0x2e00, v4
	v_ashrrev_i32_e32 v7, 31, v6
	v_lshl_add_u64 v[86:87], v[6:7], 2, s[40:41]
	v_add_u32_e32 v6, 0x3000, v4
	v_ashrrev_i32_e32 v7, 31, v6
	v_lshl_add_u64 v[88:89], v[6:7], 2, s[40:41]
	v_add_u32_e32 v6, 0x3200, v4
	v_ashrrev_i32_e32 v7, 31, v6
	v_lshl_add_u64 v[90:91], v[6:7], 2, s[40:41]
	v_add_u32_e32 v6, 0x3400, v4
	v_ashrrev_i32_e32 v7, 31, v6
	v_lshl_add_u64 v[92:93], v[6:7], 2, s[40:41]
	v_add_u32_e32 v6, 0x3600, v4
	v_ashrrev_i32_e32 v7, 31, v6
	v_lshl_add_u64 v[94:95], v[6:7], 2, s[40:41]
	v_add_u32_e32 v6, 0x3800, v4
	v_ashrrev_i32_e32 v7, 31, v6
	v_lshl_add_u64 v[96:97], v[6:7], 2, s[40:41]
	v_add_u32_e32 v6, 0x3a00, v4
	v_ashrrev_i32_e32 v7, 31, v6
	v_lshl_add_u64 v[98:99], v[6:7], 2, s[40:41]
	v_add_u32_e32 v6, 0x3c00, v4
	v_lshl_add_u64 v[10:11], v[4:5], 2, s[40:41]
	v_ashrrev_i32_e32 v7, 31, v6
	v_lshl_add_u64 v[172:173], v[6:7], 2, s[40:41]
	s_nop 0
	s_nop 0
	s_nop 0
	s_nop 0
	s_nop 0
	s_nop 0
	s_nop 0
	s_nop 0
	s_nop 0
	s_nop 0
	s_nop 0
	s_nop 0
	s_nop 0
	s_nop 0
	s_nop 0
	s_nop 0
	s_nop 0
	s_nop 0
	s_nop 0
	s_nop 0
	s_nop 0
	s_nop 0
	s_nop 0
	s_nop 0
	s_nop 0
	s_nop 0
	s_nop 0
	s_nop 0
	s_nop 0
	s_nop 0
	s_nop 0
	s_nop 0
	s_nop 0
	s_nop 0
	s_nop 0
	s_nop 0
	s_nop 0
	s_nop 0
	s_nop 0
	s_nop 0
	s_nop 0
	s_nop 0
	s_nop 0
	s_nop 0
	s_nop 0
	s_nop 0
	s_nop 0
	s_nop 0
	s_nop 0
	s_nop 0
	s_nop 0
	s_nop 0
	s_nop 0
	s_nop 0
	s_nop 0
	s_nop 0
	s_nop 0
	s_nop 0
	s_nop 0
	s_nop 0
	v_and_b32_e32 v175, 0xffff0000, v25
	v_lshlrev_b32_e32 v154, 16, v29
	v_and_b32_e32 v155, 0xffff0000, v29
	v_lshlrev_b32_e32 v152, 16, v27
	v_and_b32_e32 v153, 0xffff0000, v27
	v_lshlrev_b32_e32 v150, 16, v55
	v_and_b32_e32 v151, 0xffff0000, v55
	v_lshlrev_b32_e32 v148, 16, v49
	v_and_b32_e32 v149, 0xffff0000, v49
	v_lshlrev_b32_e32 v144, 16, v59
	v_and_b32_e32 v145, 0xffff0000, v59
	v_lshlrev_b32_e32 v140, 16, v57
	v_and_b32_e32 v141, 0xffff0000, v57
	v_lshlrev_b32_e32 v146, 16, v63
	v_and_b32_e32 v147, 0xffff0000, v63
	v_lshlrev_b32_e32 v142, 16, v61
	v_and_b32_e32 v143, 0xffff0000, v61
	v_lshlrev_b32_e32 v138, 16, v67
	v_and_b32_e32 v139, 0xffff0000, v67
	v_lshlrev_b32_e32 v136, 16, v65
	v_and_b32_e32 v137, 0xffff0000, v65
	v_lshlrev_b32_e32 v134, 16, v71
	v_and_b32_e32 v135, 0xffff0000, v71
	v_lshlrev_b32_e32 v100, 16, v69
	v_and_b32_e32 v101, 0xffff0000, v69
	v_lshlrev_b32_e32 v78, 16, v73
	v_and_b32_e32 v79, 0xffff0000, v73
	v_lshlrev_b32_e32 v48, 16, v75
	v_and_b32_e32 v49, 0xffff0000, v75
	v_lshlrev_b32_e32 v28, 16, v115
	v_and_b32_e32 v29, 0xffff0000, v115
	v_lshlrev_b32_e32 v26, 16, v113
	v_and_b32_e32 v27, 0xffff0000, v113
	v_lshlrev_b32_e32 v24, 16, v121
	v_and_b32_e32 v25, 0xffff0000, v121
	v_lshlrev_b32_e32 v74, 16, v119
	v_and_b32_e32 v75, 0xffff0000, v119
	v_lshlrev_b32_e32 v72, 16, v125
	v_and_b32_e32 v73, 0xffff0000, v125
	v_lshlrev_b32_e32 v70, 16, v123
	v_and_b32_e32 v71, 0xffff0000, v123
	v_lshlrev_b32_e32 v68, 16, v129
	v_and_b32_e32 v69, 0xffff0000, v129
	v_lshlrev_b32_e32 v66, 16, v127
	v_and_b32_e32 v67, 0xffff0000, v127
	v_lshlrev_b32_e32 v64, 16, v133
	v_and_b32_e32 v65, 0xffff0000, v133
	v_lshlrev_b32_e32 v62, 16, v131
	v_and_b32_e32 v63, 0xffff0000, v131
	v_lshlrev_b32_e32 v60, 16, v164
	v_and_b32_e32 v61, 0xffff0000, v164
	v_lshlrev_b32_e32 v58, 16, v163
	v_and_b32_e32 v59, 0xffff0000, v163
	v_lshlrev_b32_e32 v56, 16, v167
	v_and_b32_e32 v57, 0xffff0000, v167
	v_lshlrev_b32_e32 v54, 16, v166
	v_and_b32_e32 v55, 0xffff0000, v166
	v_lshlrev_b32_e32 v124, 16, v169
	v_and_b32_e32 v125, 0xffff0000, v169
	s_waitcnt vmcnt(46)
; DI float bflo(unsigned u) { return __uint_as_float(u << 16); }
; DI float bfhi(unsigned u) { return __uint_as_float(u & 0xffff0000u); }
; DI void conv_item(const Params& p, int item, char* smem) {
;     ...
;   for (int pass = 0; pass < 2; ++pass) {
;     float w[31];
; #pragma unroll
;     for (int k = 0; k < 31; ++k) w[k] = p.w_dw[k * 512 + c0 + pass];
; #pragma unroll
;     for (int tl = 0; tl < 16; ++tl) {
;       float a0 = pass ? bias.y : bias.x;
; #pragma unroll
;       for (int k = 0; k < 31; ++k) a0 += w[k] * (pass ? bfhi(rowv[tl + k]) : bflo(rowv[tl + k]));
;       cs[tl * 520 + c0 + pass] = a0;
;     }
	v_lshlrev_b32_e32 v122, 16, v171
	v_and_b32_e32 v123, 0xffff0000, v171
	s_waitcnt vmcnt(45)
	v_lshlrev_b32_e32 v132, 16, v170
	v_and_b32_e32 v133, 0xffff0000, v170
	s_waitcnt vmcnt(44)
	v_lshlrev_b32_e32 v130, 16, v168
	v_and_b32_e32 v131, 0xffff0000, v168
	s_waitcnt vmcnt(43)
	v_lshlrev_b32_e32 v128, 16, v165
	v_and_b32_e32 v129, 0xffff0000, v165
	s_waitcnt vmcnt(42)
	v_lshlrev_b32_e32 v126, 16, v162
	s_waitcnt vmcnt(30)
	v_pk_fma_f32 v[174:175], v[176:177], v[174:175], v[2:3]
	v_and_b32_e32 v127, 0xffff0000, v162
	s_waitcnt vmcnt(29)
	v_pk_fma_f32 v[174:175], v[178:179], v[154:155], v[174:175]
	v_pk_fma_f32 v[154:155], v[176:177], v[154:155], v[2:3]
	s_waitcnt vmcnt(28)
	v_pk_fma_f32 v[174:175], v[180:181], v[152:153], v[174:175]
	v_pk_fma_f32 v[154:155], v[178:179], v[152:153], v[154:155]
	v_pk_fma_f32 v[152:153], v[176:177], v[152:153], v[2:3]
	s_waitcnt vmcnt(27)
	v_pk_fma_f32 v[174:175], v[182:183], v[150:151], v[174:175]
	v_pk_fma_f32 v[154:155], v[180:181], v[150:151], v[154:155]
	v_pk_fma_f32 v[152:153], v[178:179], v[150:151], v[152:153]
	v_pk_fma_f32 v[150:151], v[176:177], v[150:151], v[2:3]
	s_waitcnt vmcnt(26)
	v_pk_fma_f32 v[174:175], v[184:185], v[148:149], v[174:175]
	v_pk_fma_f32 v[154:155], v[182:183], v[148:149], v[154:155]
	v_pk_fma_f32 v[152:153], v[180:181], v[148:149], v[152:153]
	v_pk_fma_f32 v[150:151], v[178:179], v[148:149], v[150:151]
	v_pk_fma_f32 v[148:149], v[176:177], v[148:149], v[2:3]
	s_waitcnt vmcnt(25)
	v_pk_fma_f32 v[174:175], v[186:187], v[144:145], v[174:175]
	v_pk_fma_f32 v[154:155], v[184:185], v[144:145], v[154:155]
	v_pk_fma_f32 v[152:153], v[182:183], v[144:145], v[152:153]
	v_pk_fma_f32 v[150:151], v[180:181], v[144:145], v[150:151]
	v_pk_fma_f32 v[148:149], v[178:179], v[144:145], v[148:149]
	v_pk_fma_f32 v[144:145], v[176:177], v[144:145], v[2:3]
	s_waitcnt vmcnt(24)
	v_pk_fma_f32 v[174:175], v[188:189], v[140:141], v[174:175]
	v_pk_fma_f32 v[154:155], v[186:187], v[140:141], v[154:155]
	v_pk_fma_f32 v[152:153], v[184:185], v[140:141], v[152:153]
	v_pk_fma_f32 v[150:151], v[182:183], v[140:141], v[150:151]
	v_pk_fma_f32 v[148:149], v[180:181], v[140:141], v[148:149]
	v_pk_fma_f32 v[144:145], v[178:179], v[140:141], v[144:145]
	v_pk_fma_f32 v[140:141], v[176:177], v[140:141], v[2:3]
	v_lshlrev_b32_e32 v120, 16, v161
	v_pk_fma_f32 v[140:141], v[178:179], v[146:147], v[140:141]
	v_and_b32_e32 v121, 0xffff0000, v161
	v_pk_fma_f32 v[140:141], v[180:181], v[142:143], v[140:141]
	v_lshlrev_b32_e32 v118, 16, v160
	v_pk_fma_f32 v[140:141], v[182:183], v[138:139], v[140:141]
	v_and_b32_e32 v119, 0xffff0000, v160
	v_pk_fma_f32 v[140:141], v[184:185], v[136:137], v[140:141]
	v_lshl_add_u32 v172, v4, 2, s33
	v_pk_fma_f32 v[140:141], v[186:187], v[134:135], v[140:141]
	v_lshlrev_b32_e32 v116, 16, v117
	v_pk_fma_f32 v[140:141], v[188:189], v[100:101], v[140:141]
	v_and_b32_e32 v117, 0xffff0000, v117
	s_waitcnt vmcnt(23)
	v_pk_fma_f32 v[140:141], v[190:191], v[78:79], v[140:141]
	v_pk_fma_f32 v[174:175], v[190:191], v[146:147], v[174:175]
	s_waitcnt vmcnt(22)
	v_pk_fma_f32 v[140:141], v[192:193], v[48:49], v[140:141]
	v_pk_fma_f32 v[154:155], v[188:189], v[146:147], v[154:155]
	s_waitcnt vmcnt(21)
	v_pk_fma_f32 v[140:141], v[194:195], v[28:29], v[140:141]
	v_pk_fma_f32 v[152:153], v[186:187], v[146:147], v[152:153]
	s_waitcnt vmcnt(20)
	v_pk_fma_f32 v[140:141], v[196:197], v[26:27], v[140:141]
	v_pk_fma_f32 v[150:151], v[184:185], v[146:147], v[150:151]
	s_waitcnt vmcnt(19)
	v_pk_fma_f32 v[140:141], v[198:199], v[24:25], v[140:141]
	v_pk_fma_f32 v[148:149], v[182:183], v[146:147], v[148:149]
	s_waitcnt vmcnt(18)
	v_pk_fma_f32 v[140:141], v[200:201], v[74:75], v[140:141]
	v_pk_fma_f32 v[144:145], v[180:181], v[146:147], v[144:145]
	s_waitcnt vmcnt(17)
	v_pk_fma_f32 v[140:141], v[202:203], v[72:73], v[140:141]
	v_pk_fma_f32 v[174:175], v[192:193], v[142:143], v[174:175]
	s_waitcnt vmcnt(16)
	v_pk_fma_f32 v[140:141], v[204:205], v[70:71], v[140:141]
	v_pk_fma_f32 v[154:155], v[190:191], v[142:143], v[154:155]
	s_waitcnt vmcnt(15)
	v_pk_fma_f32 v[140:141], v[206:207], v[68:69], v[140:141]
	v_pk_fma_f32 v[152:153], v[188:189], v[142:143], v[152:153]
	s_waitcnt vmcnt(14)
	v_pk_fma_f32 v[140:141], v[208:209], v[66:67], v[140:141]
	v_pk_fma_f32 v[150:151], v[186:187], v[142:143], v[150:151]
	s_waitcnt vmcnt(13)
	v_pk_fma_f32 v[140:141], v[214:215], v[64:65], v[140:141]
	v_pk_fma_f32 v[148:149], v[184:185], v[142:143], v[148:149]
	s_waitcnt vmcnt(12)
	v_pk_fma_f32 v[140:141], v[216:217], v[62:63], v[140:141]
	v_pk_fma_f32 v[144:145], v[182:183], v[142:143], v[144:145]
	s_waitcnt vmcnt(11)
	v_pk_fma_f32 v[140:141], v[218:219], v[60:61], v[140:141]
	v_pk_fma_f32 v[174:175], v[194:195], v[138:139], v[174:175]
	s_waitcnt vmcnt(10)
	v_pk_fma_f32 v[140:141], v[220:221], v[58:59], v[140:141]
	v_pk_fma_f32 v[154:155], v[192:193], v[138:139], v[154:155]
	s_waitcnt vmcnt(9)
	v_pk_fma_f32 v[140:141], v[222:223], v[56:57], v[140:141]
	v_pk_fma_f32 v[152:153], v[190:191], v[138:139], v[152:153]
	s_waitcnt vmcnt(8)
	v_pk_fma_f32 v[140:141], v[224:225], v[54:55], v[140:141]
	v_pk_fma_f32 v[150:151], v[188:189], v[138:139], v[150:151]
	s_waitcnt vmcnt(7)
	v_pk_fma_f32 v[140:141], v[226:227], v[124:125], v[140:141]
	v_pk_fma_f32 v[148:149], v[186:187], v[138:139], v[148:149]
	s_waitcnt vmcnt(6)
	v_pk_fma_f32 v[140:141], v[228:229], v[122:123], v[140:141]
	v_pk_fma_f32 v[144:145], v[184:185], v[138:139], v[144:145]
	s_waitcnt vmcnt(5)
	v_pk_fma_f32 v[140:141], v[230:231], v[132:133], v[140:141]
	v_pk_fma_f32 v[174:175], v[196:197], v[136:137], v[174:175]
	s_waitcnt vmcnt(4)
; DI float bflo(unsigned u) { return __uint_as_float(u << 16); }
; DI float bfhi(unsigned u) { return __uint_as_float(u & 0xffff0000u); }
; DI void conv_item(const Params& p, int item, char* smem) {
;     ...
; #pragma unroll
;     for (int tl = 0; tl < 16; ++tl) {
;       float a0 = pass ? bias.y : bias.x;
; #pragma unroll
;       for (int k = 0; k < 31; ++k) a0 += w[k] * (pass ? bfhi(rowv[tl + k]) : bflo(rowv[tl + k]));
;       cs[tl * 520 + c0 + pass] = a0;
;     }
	v_pk_fma_f32 v[140:141], v[232:233], v[130:131], v[140:141]
	v_pk_fma_f32 v[154:155], v[194:195], v[136:137], v[154:155]
	s_waitcnt vmcnt(3)
	v_pk_fma_f32 v[140:141], v[234:235], v[128:129], v[140:141]
	v_pk_fma_f32 v[152:153], v[192:193], v[136:137], v[152:153]
	s_waitcnt vmcnt(2)
	v_pk_fma_f32 v[140:141], v[236:237], v[126:127], v[140:141]
	v_pk_fma_f32 v[150:151], v[190:191], v[136:137], v[150:151]
	s_waitcnt vmcnt(1)
	v_pk_fma_f32 v[140:141], v[238:239], v[120:121], v[140:141]
	v_pk_fma_f32 v[148:149], v[188:189], v[136:137], v[148:149]
	s_waitcnt vmcnt(0)
	v_pk_fma_f32 v[140:141], v[240:241], v[118:119], v[140:141]
	ds_write_b64 v172, v[140:141] offset:12480
	v_pk_fma_f32 v[140:141], v[176:177], v[146:147], v[2:3]
	v_pk_fma_f32 v[144:145], v[186:187], v[136:137], v[144:145]
	v_pk_fma_f32 v[140:141], v[178:179], v[142:143], v[140:141]
	v_pk_fma_f32 v[174:175], v[198:199], v[134:135], v[174:175]
	v_pk_fma_f32 v[140:141], v[180:181], v[138:139], v[140:141]
	v_pk_fma_f32 v[154:155], v[196:197], v[134:135], v[154:155]
	v_pk_fma_f32 v[140:141], v[182:183], v[136:137], v[140:141]
	v_pk_fma_f32 v[152:153], v[194:195], v[134:135], v[152:153]
	v_pk_fma_f32 v[140:141], v[184:185], v[134:135], v[140:141]
	v_pk_fma_f32 v[150:151], v[192:193], v[134:135], v[150:151]
	v_pk_fma_f32 v[140:141], v[186:187], v[100:101], v[140:141]
	v_pk_fma_f32 v[148:149], v[190:191], v[134:135], v[148:149]
	v_pk_fma_f32 v[140:141], v[188:189], v[78:79], v[140:141]
	v_pk_fma_f32 v[144:145], v[188:189], v[134:135], v[144:145]
	v_pk_fma_f32 v[140:141], v[190:191], v[48:49], v[140:141]
	v_pk_fma_f32 v[174:175], v[200:201], v[100:101], v[174:175]
	v_pk_fma_f32 v[140:141], v[192:193], v[28:29], v[140:141]
	v_pk_fma_f32 v[154:155], v[198:199], v[100:101], v[154:155]
	v_pk_fma_f32 v[140:141], v[194:195], v[26:27], v[140:141]
	v_pk_fma_f32 v[152:153], v[196:197], v[100:101], v[152:153]
	v_pk_fma_f32 v[140:141], v[196:197], v[24:25], v[140:141]
	v_pk_fma_f32 v[150:151], v[194:195], v[100:101], v[150:151]
	v_pk_fma_f32 v[140:141], v[198:199], v[74:75], v[140:141]
	v_pk_fma_f32 v[148:149], v[192:193], v[100:101], v[148:149]
	v_pk_fma_f32 v[140:141], v[200:201], v[72:73], v[140:141]
	v_pk_fma_f32 v[144:145], v[190:191], v[100:101], v[144:145]
	v_pk_fma_f32 v[140:141], v[202:203], v[70:71], v[140:141]
	v_pk_fma_f32 v[174:175], v[202:203], v[78:79], v[174:175]
	v_pk_fma_f32 v[140:141], v[204:205], v[68:69], v[140:141]
	v_pk_fma_f32 v[154:155], v[200:201], v[78:79], v[154:155]
	v_pk_fma_f32 v[140:141], v[206:207], v[66:67], v[140:141]
	v_pk_fma_f32 v[152:153], v[198:199], v[78:79], v[152:153]
	v_pk_fma_f32 v[140:141], v[208:209], v[64:65], v[140:141]
	v_pk_fma_f32 v[150:151], v[196:197], v[78:79], v[150:151]
	v_pk_fma_f32 v[140:141], v[214:215], v[62:63], v[140:141]
	v_pk_fma_f32 v[148:149], v[194:195], v[78:79], v[148:149]
	v_pk_fma_f32 v[140:141], v[216:217], v[60:61], v[140:141]
	v_pk_fma_f32 v[144:145], v[192:193], v[78:79], v[144:145]
	v_pk_fma_f32 v[140:141], v[218:219], v[58:59], v[140:141]
	v_pk_fma_f32 v[174:175], v[204:205], v[48:49], v[174:175]
	v_pk_fma_f32 v[140:141], v[220:221], v[56:57], v[140:141]
	v_pk_fma_f32 v[154:155], v[202:203], v[48:49], v[154:155]
	v_pk_fma_f32 v[140:141], v[222:223], v[54:55], v[140:141]
	v_pk_fma_f32 v[152:153], v[200:201], v[48:49], v[152:153]
	v_pk_fma_f32 v[140:141], v[224:225], v[124:125], v[140:141]
	v_pk_fma_f32 v[150:151], v[198:199], v[48:49], v[150:151]
	v_pk_fma_f32 v[140:141], v[226:227], v[122:123], v[140:141]
	v_pk_fma_f32 v[148:149], v[196:197], v[48:49], v[148:149]
	v_pk_fma_f32 v[140:141], v[228:229], v[132:133], v[140:141]
	v_pk_fma_f32 v[144:145], v[194:195], v[48:49], v[144:145]
	v_pk_fma_f32 v[140:141], v[230:231], v[130:131], v[140:141]
	v_pk_fma_f32 v[144:145], v[196:197], v[28:29], v[144:145]
	v_pk_fma_f32 v[140:141], v[232:233], v[128:129], v[140:141]
	v_pk_fma_f32 v[148:149], v[198:199], v[28:29], v[148:149]
	v_pk_fma_f32 v[140:141], v[234:235], v[126:127], v[140:141]
	v_pk_fma_f32 v[144:145], v[198:199], v[26:27], v[144:145]
	v_pk_fma_f32 v[140:141], v[236:237], v[120:121], v[140:141]
	v_pk_fma_f32 v[150:151], v[200:201], v[28:29], v[150:151]
	v_pk_fma_f32 v[140:141], v[238:239], v[118:119], v[140:141]
	v_pk_fma_f32 v[148:149], v[200:201], v[26:27], v[148:149]
	v_pk_fma_f32 v[140:141], v[240:241], v[116:117], v[140:141]
	ds_write_b64 v172, v[140:141] offset:14560
	v_pk_fma_f32 v[140:141], v[176:177], v[142:143], v[2:3]
	v_pk_fma_f32 v[144:145], v[200:201], v[24:25], v[144:145]
	v_pk_fma_f32 v[140:141], v[178:179], v[138:139], v[140:141]
	v_pk_fma_f32 v[138:139], v[176:177], v[138:139], v[2:3]
	v_pk_fma_f32 v[140:141], v[180:181], v[136:137], v[140:141]
	v_pk_fma_f32 v[138:139], v[178:179], v[136:137], v[138:139]
	v_pk_fma_f32 v[136:137], v[176:177], v[136:137], v[2:3]
	v_pk_fma_f32 v[140:141], v[182:183], v[134:135], v[140:141]
	v_pk_fma_f32 v[138:139], v[180:181], v[134:135], v[138:139]
	v_pk_fma_f32 v[136:137], v[178:179], v[134:135], v[136:137]
	v_pk_fma_f32 v[134:135], v[176:177], v[134:135], v[2:3]
	v_pk_fma_f32 v[140:141], v[184:185], v[100:101], v[140:141]
	v_pk_fma_f32 v[138:139], v[182:183], v[100:101], v[138:139]
	v_pk_fma_f32 v[136:137], v[180:181], v[100:101], v[136:137]
	v_pk_fma_f32 v[134:135], v[178:179], v[100:101], v[134:135]
	v_pk_fma_f32 v[100:101], v[176:177], v[100:101], v[2:3]
	v_pk_fma_f32 v[140:141], v[186:187], v[78:79], v[140:141]
	v_pk_fma_f32 v[138:139], v[184:185], v[78:79], v[138:139]
	v_pk_fma_f32 v[136:137], v[182:183], v[78:79], v[136:137]
	v_pk_fma_f32 v[134:135], v[180:181], v[78:79], v[134:135]
	v_pk_fma_f32 v[100:101], v[178:179], v[78:79], v[100:101]
; DI float bflo(unsigned u) { return __uint_as_float(u << 16); }
; DI float bfhi(unsigned u) { return __uint_as_float(u & 0xffff0000u); }
; DI void conv_item(const Params& p, int item, char* smem) {
;     ...
; #pragma unroll
;     for (int tl = 0; tl < 16; ++tl) {
;       float a0 = pass ? bias.y : bias.x;
; #pragma unroll
;       for (int k = 0; k < 31; ++k) a0 += w[k] * (pass ? bfhi(rowv[tl + k]) : bflo(rowv[tl + k]));
;       cs[tl * 520 + c0 + pass] = a0;
;     }
	v_pk_fma_f32 v[78:79], v[176:177], v[78:79], v[2:3]
	v_pk_fma_f32 v[140:141], v[188:189], v[48:49], v[140:141]
	v_pk_fma_f32 v[138:139], v[186:187], v[48:49], v[138:139]
	v_pk_fma_f32 v[136:137], v[184:185], v[48:49], v[136:137]
	v_pk_fma_f32 v[134:135], v[182:183], v[48:49], v[134:135]
	v_pk_fma_f32 v[100:101], v[180:181], v[48:49], v[100:101]
	v_pk_fma_f32 v[78:79], v[178:179], v[48:49], v[78:79]
	v_pk_fma_f32 v[48:49], v[176:177], v[48:49], v[2:3]
	v_pk_fma_f32 v[2:3], v[176:177], v[28:29], v[2:3]
	v_pk_fma_f32 v[48:49], v[178:179], v[28:29], v[48:49]
	v_pk_fma_f32 v[2:3], v[178:179], v[26:27], v[2:3]
	v_pk_fma_f32 v[78:79], v[180:181], v[28:29], v[78:79]
	v_pk_fma_f32 v[48:49], v[180:181], v[26:27], v[48:49]
	v_pk_fma_f32 v[2:3], v[180:181], v[24:25], v[2:3]
	v_pk_fma_f32 v[100:101], v[182:183], v[28:29], v[100:101]
	v_pk_fma_f32 v[78:79], v[182:183], v[26:27], v[78:79]
	v_pk_fma_f32 v[48:49], v[182:183], v[24:25], v[48:49]
	v_pk_fma_f32 v[2:3], v[182:183], v[74:75], v[2:3]
	v_pk_fma_f32 v[134:135], v[184:185], v[28:29], v[134:135]
	v_pk_fma_f32 v[100:101], v[184:185], v[26:27], v[100:101]
	v_pk_fma_f32 v[78:79], v[184:185], v[24:25], v[78:79]
	v_pk_fma_f32 v[48:49], v[184:185], v[74:75], v[48:49]
	v_pk_fma_f32 v[2:3], v[184:185], v[72:73], v[2:3]
	v_pk_fma_f32 v[136:137], v[186:187], v[28:29], v[136:137]
	v_pk_fma_f32 v[134:135], v[186:187], v[26:27], v[134:135]
	v_pk_fma_f32 v[100:101], v[186:187], v[24:25], v[100:101]
	v_pk_fma_f32 v[78:79], v[186:187], v[74:75], v[78:79]
	v_pk_fma_f32 v[48:49], v[186:187], v[72:73], v[48:49]
	v_pk_fma_f32 v[2:3], v[186:187], v[70:71], v[2:3]
	v_pk_fma_f32 v[138:139], v[188:189], v[28:29], v[138:139]
	v_pk_fma_f32 v[136:137], v[188:189], v[26:27], v[136:137]
	v_pk_fma_f32 v[134:135], v[188:189], v[24:25], v[134:135]
	v_pk_fma_f32 v[100:101], v[188:189], v[74:75], v[100:101]
	v_pk_fma_f32 v[78:79], v[188:189], v[72:73], v[78:79]
	v_pk_fma_f32 v[48:49], v[188:189], v[70:71], v[48:49]
	v_pk_fma_f32 v[2:3], v[188:189], v[68:69], v[2:3]
	v_pk_fma_f32 v[140:141], v[190:191], v[28:29], v[140:141]
	v_pk_fma_f32 v[138:139], v[190:191], v[26:27], v[138:139]
	v_pk_fma_f32 v[136:137], v[190:191], v[24:25], v[136:137]
	v_pk_fma_f32 v[134:135], v[190:191], v[74:75], v[134:135]
	v_pk_fma_f32 v[100:101], v[190:191], v[72:73], v[100:101]
	v_pk_fma_f32 v[78:79], v[190:191], v[70:71], v[78:79]
	v_pk_fma_f32 v[48:49], v[190:191], v[68:69], v[48:49]
	v_pk_fma_f32 v[2:3], v[190:191], v[66:67], v[2:3]
	v_pk_fma_f32 v[140:141], v[192:193], v[26:27], v[140:141]
	v_pk_fma_f32 v[138:139], v[192:193], v[24:25], v[138:139]
	v_pk_fma_f32 v[136:137], v[192:193], v[74:75], v[136:137]
	v_pk_fma_f32 v[134:135], v[192:193], v[72:73], v[134:135]
	v_pk_fma_f32 v[100:101], v[192:193], v[70:71], v[100:101]
	v_pk_fma_f32 v[78:79], v[192:193], v[68:69], v[78:79]
	v_pk_fma_f32 v[48:49], v[192:193], v[66:67], v[48:49]
	v_pk_fma_f32 v[2:3], v[192:193], v[64:65], v[2:3]
	v_pk_fma_f32 v[140:141], v[194:195], v[24:25], v[140:141]
	v_pk_fma_f32 v[138:139], v[194:195], v[74:75], v[138:139]
	v_pk_fma_f32 v[136:137], v[194:195], v[72:73], v[136:137]
	v_pk_fma_f32 v[134:135], v[194:195], v[70:71], v[134:135]
	v_pk_fma_f32 v[100:101], v[194:195], v[68:69], v[100:101]
	v_pk_fma_f32 v[78:79], v[194:195], v[66:67], v[78:79]
	v_pk_fma_f32 v[48:49], v[194:195], v[64:65], v[48:49]
	v_pk_fma_f32 v[2:3], v[194:195], v[62:63], v[2:3]
	v_pk_fma_f32 v[140:141], v[196:197], v[74:75], v[140:141]
	v_pk_fma_f32 v[138:139], v[196:197], v[72:73], v[138:139]
	v_pk_fma_f32 v[136:137], v[196:197], v[70:71], v[136:137]
	v_pk_fma_f32 v[134:135], v[196:197], v[68:69], v[134:135]
	v_pk_fma_f32 v[100:101], v[196:197], v[66:67], v[100:101]
	v_pk_fma_f32 v[78:79], v[196:197], v[64:65], v[78:79]
	v_pk_fma_f32 v[48:49], v[196:197], v[62:63], v[48:49]
	v_pk_fma_f32 v[2:3], v[196:197], v[60:61], v[2:3]
	v_pk_fma_f32 v[140:141], v[198:199], v[72:73], v[140:141]
	v_pk_fma_f32 v[138:139], v[198:199], v[70:71], v[138:139]
	v_pk_fma_f32 v[136:137], v[198:199], v[68:69], v[136:137]
	v_pk_fma_f32 v[134:135], v[198:199], v[66:67], v[134:135]
	v_pk_fma_f32 v[100:101], v[198:199], v[64:65], v[100:101]
	v_pk_fma_f32 v[78:79], v[198:199], v[62:63], v[78:79]
	v_pk_fma_f32 v[48:49], v[198:199], v[60:61], v[48:49]
	v_pk_fma_f32 v[2:3], v[198:199], v[58:59], v[2:3]
	v_pk_fma_f32 v[140:141], v[200:201], v[70:71], v[140:141]
	v_pk_fma_f32 v[138:139], v[200:201], v[68:69], v[138:139]
	v_pk_fma_f32 v[136:137], v[200:201], v[66:67], v[136:137]
	v_pk_fma_f32 v[134:135], v[200:201], v[64:65], v[134:135]
	v_pk_fma_f32 v[100:101], v[200:201], v[62:63], v[100:101]
	v_pk_fma_f32 v[78:79], v[200:201], v[60:61], v[78:79]
	v_pk_fma_f32 v[48:49], v[200:201], v[58:59], v[48:49]
	v_pk_fma_f32 v[2:3], v[200:201], v[56:57], v[2:3]
	v_pk_fma_f32 v[152:153], v[202:203], v[28:29], v[152:153]
	v_pk_fma_f32 v[150:151], v[202:203], v[26:27], v[150:151]
	v_pk_fma_f32 v[148:149], v[202:203], v[24:25], v[148:149]
	v_pk_fma_f32 v[144:145], v[202:203], v[74:75], v[144:145]
	v_pk_fma_f32 v[140:141], v[202:203], v[68:69], v[140:141]
	v_pk_fma_f32 v[138:139], v[202:203], v[66:67], v[138:139]
	v_pk_fma_f32 v[136:137], v[202:203], v[64:65], v[136:137]
	v_pk_fma_f32 v[134:135], v[202:203], v[62:63], v[134:135]
	v_pk_fma_f32 v[100:101], v[202:203], v[60:61], v[100:101]
	v_pk_fma_f32 v[78:79], v[202:203], v[58:59], v[78:79]
	v_pk_fma_f32 v[48:49], v[202:203], v[56:57], v[48:49]
	v_pk_fma_f32 v[2:3], v[202:203], v[54:55], v[2:3]
	v_pk_fma_f32 v[154:155], v[204:205], v[28:29], v[154:155]
	v_pk_fma_f32 v[152:153], v[204:205], v[26:27], v[152:153]
	v_pk_fma_f32 v[150:151], v[204:205], v[24:25], v[150:151]
; DI float bflo(unsigned u) { return __uint_as_float(u << 16); }
; DI float bfhi(unsigned u) { return __uint_as_float(u & 0xffff0000u); }
; DI void conv_item(const Params& p, int item, char* smem) {
;     ...
; #pragma unroll
;     for (int tl = 0; tl < 16; ++tl) {
;       float a0 = pass ? bias.y : bias.x;
; #pragma unroll
;       for (int k = 0; k < 31; ++k) a0 += w[k] * (pass ? bfhi(rowv[tl + k]) : bflo(rowv[tl + k]));
;       cs[tl * 520 + c0 + pass] = a0;
;     }
	v_pk_fma_f32 v[148:149], v[204:205], v[74:75], v[148:149]
	v_pk_fma_f32 v[144:145], v[204:205], v[72:73], v[144:145]
	v_pk_fma_f32 v[140:141], v[204:205], v[66:67], v[140:141]
	v_pk_fma_f32 v[138:139], v[204:205], v[64:65], v[138:139]
	v_pk_fma_f32 v[136:137], v[204:205], v[62:63], v[136:137]
	v_pk_fma_f32 v[134:135], v[204:205], v[60:61], v[134:135]
	v_pk_fma_f32 v[100:101], v[204:205], v[58:59], v[100:101]
	v_pk_fma_f32 v[78:79], v[204:205], v[56:57], v[78:79]
	v_pk_fma_f32 v[48:49], v[204:205], v[54:55], v[48:49]
	v_pk_fma_f32 v[2:3], v[204:205], v[124:125], v[2:3]
	v_pk_fma_f32 v[174:175], v[206:207], v[28:29], v[174:175]
	v_pk_fma_f32 v[154:155], v[206:207], v[26:27], v[154:155]
	v_pk_fma_f32 v[152:153], v[206:207], v[24:25], v[152:153]
	v_pk_fma_f32 v[150:151], v[206:207], v[74:75], v[150:151]
	v_pk_fma_f32 v[148:149], v[206:207], v[72:73], v[148:149]
	v_pk_fma_f32 v[144:145], v[206:207], v[70:71], v[144:145]
	v_pk_fma_f32 v[140:141], v[206:207], v[64:65], v[140:141]
	v_pk_fma_f32 v[138:139], v[206:207], v[62:63], v[138:139]
	v_pk_fma_f32 v[136:137], v[206:207], v[60:61], v[136:137]
	v_pk_fma_f32 v[134:135], v[206:207], v[58:59], v[134:135]
	v_pk_fma_f32 v[100:101], v[206:207], v[56:57], v[100:101]
	v_pk_fma_f32 v[78:79], v[206:207], v[54:55], v[78:79]
	v_pk_fma_f32 v[48:49], v[206:207], v[124:125], v[48:49]
	v_pk_fma_f32 v[2:3], v[206:207], v[122:123], v[2:3]
	v_pk_fma_f32 v[174:175], v[208:209], v[26:27], v[174:175]
	v_pk_fma_f32 v[154:155], v[208:209], v[24:25], v[154:155]
	v_pk_fma_f32 v[152:153], v[208:209], v[74:75], v[152:153]
	v_pk_fma_f32 v[150:151], v[208:209], v[72:73], v[150:151]
	v_pk_fma_f32 v[148:149], v[208:209], v[70:71], v[148:149]
	v_pk_fma_f32 v[144:145], v[208:209], v[68:69], v[144:145]
	v_pk_fma_f32 v[140:141], v[208:209], v[62:63], v[140:141]
	v_pk_fma_f32 v[138:139], v[208:209], v[60:61], v[138:139]
	v_pk_fma_f32 v[136:137], v[208:209], v[58:59], v[136:137]
	v_pk_fma_f32 v[134:135], v[208:209], v[56:57], v[134:135]
	v_pk_fma_f32 v[100:101], v[208:209], v[54:55], v[100:101]
	v_pk_fma_f32 v[78:79], v[208:209], v[124:125], v[78:79]
	v_pk_fma_f32 v[48:49], v[208:209], v[122:123], v[48:49]
	v_pk_fma_f32 v[2:3], v[208:209], v[132:133], v[2:3]
	v_pk_fma_f32 v[174:175], v[214:215], v[24:25], v[174:175]
	v_pk_fma_f32 v[154:155], v[214:215], v[74:75], v[154:155]
	v_pk_fma_f32 v[152:153], v[214:215], v[72:73], v[152:153]
	v_pk_fma_f32 v[150:151], v[214:215], v[70:71], v[150:151]
	v_pk_fma_f32 v[148:149], v[214:215], v[68:69], v[148:149]
	v_pk_fma_f32 v[144:145], v[214:215], v[66:67], v[144:145]
	v_pk_fma_f32 v[140:141], v[214:215], v[60:61], v[140:141]
	v_pk_fma_f32 v[138:139], v[214:215], v[58:59], v[138:139]
	v_pk_fma_f32 v[136:137], v[214:215], v[56:57], v[136:137]
	v_pk_fma_f32 v[134:135], v[214:215], v[54:55], v[134:135]
	v_pk_fma_f32 v[100:101], v[214:215], v[124:125], v[100:101]
	v_pk_fma_f32 v[78:79], v[214:215], v[122:123], v[78:79]
	v_pk_fma_f32 v[48:49], v[214:215], v[132:133], v[48:49]
	v_pk_fma_f32 v[2:3], v[214:215], v[130:131], v[2:3]
	v_pk_fma_f32 v[174:175], v[216:217], v[74:75], v[174:175]
	v_pk_fma_f32 v[154:155], v[216:217], v[72:73], v[154:155]
	v_pk_fma_f32 v[152:153], v[216:217], v[70:71], v[152:153]
	v_pk_fma_f32 v[150:151], v[216:217], v[68:69], v[150:151]
	v_pk_fma_f32 v[148:149], v[216:217], v[66:67], v[148:149]
	v_pk_fma_f32 v[144:145], v[216:217], v[64:65], v[144:145]
	v_pk_fma_f32 v[140:141], v[216:217], v[58:59], v[140:141]
	v_pk_fma_f32 v[138:139], v[216:217], v[56:57], v[138:139]
	v_pk_fma_f32 v[136:137], v[216:217], v[54:55], v[136:137]
	v_pk_fma_f32 v[134:135], v[216:217], v[124:125], v[134:135]
	v_pk_fma_f32 v[100:101], v[216:217], v[122:123], v[100:101]
	v_pk_fma_f32 v[78:79], v[216:217], v[132:133], v[78:79]
	v_pk_fma_f32 v[48:49], v[216:217], v[130:131], v[48:49]
	v_pk_fma_f32 v[2:3], v[216:217], v[128:129], v[2:3]
	v_pk_fma_f32 v[174:175], v[218:219], v[72:73], v[174:175]
	v_pk_fma_f32 v[154:155], v[218:219], v[70:71], v[154:155]
	v_pk_fma_f32 v[152:153], v[218:219], v[68:69], v[152:153]
	v_pk_fma_f32 v[150:151], v[218:219], v[66:67], v[150:151]
	v_pk_fma_f32 v[148:149], v[218:219], v[64:65], v[148:149]
	v_pk_fma_f32 v[144:145], v[218:219], v[62:63], v[144:145]
	v_pk_fma_f32 v[140:141], v[218:219], v[56:57], v[140:141]
	v_pk_fma_f32 v[138:139], v[218:219], v[54:55], v[138:139]
	v_pk_fma_f32 v[136:137], v[218:219], v[124:125], v[136:137]
	v_pk_fma_f32 v[134:135], v[218:219], v[122:123], v[134:135]
	v_pk_fma_f32 v[100:101], v[218:219], v[132:133], v[100:101]
	v_pk_fma_f32 v[78:79], v[218:219], v[130:131], v[78:79]
	v_pk_fma_f32 v[48:49], v[218:219], v[128:129], v[48:49]
	v_pk_fma_f32 v[2:3], v[218:219], v[126:127], v[2:3]
	v_pk_fma_f32 v[166:167], v[220:221], v[70:71], v[174:175]
	v_pk_fma_f32 v[154:155], v[220:221], v[68:69], v[154:155]
	v_pk_fma_f32 v[152:153], v[220:221], v[66:67], v[152:153]
	v_pk_fma_f32 v[150:151], v[220:221], v[64:65], v[150:151]
	v_pk_fma_f32 v[148:149], v[220:221], v[62:63], v[148:149]
	v_pk_fma_f32 v[144:145], v[220:221], v[60:61], v[144:145]
	v_pk_fma_f32 v[140:141], v[220:221], v[54:55], v[140:141]
	v_pk_fma_f32 v[138:139], v[220:221], v[124:125], v[138:139]
	v_pk_fma_f32 v[136:137], v[220:221], v[122:123], v[136:137]
	v_pk_fma_f32 v[134:135], v[220:221], v[132:133], v[134:135]
	v_pk_fma_f32 v[100:101], v[220:221], v[130:131], v[100:101]
	v_pk_fma_f32 v[78:79], v[220:221], v[128:129], v[78:79]
	v_pk_fma_f32 v[48:49], v[220:221], v[126:127], v[48:49]
	v_pk_fma_f32 v[2:3], v[220:221], v[120:121], v[2:3]
	v_pk_fma_f32 v[166:167], v[222:223], v[68:69], v[166:167]
	v_pk_fma_f32 v[154:155], v[222:223], v[66:67], v[154:155]
	v_pk_fma_f32 v[152:153], v[222:223], v[64:65], v[152:153]
; DI float bflo(unsigned u) { return __uint_as_float(u << 16); }
; DI float bfhi(unsigned u) { return __uint_as_float(u & 0xffff0000u); }
; DI void conv_item(const Params& p, int item, char* smem) {
;     ...
; #pragma unroll
;     for (int tl = 0; tl < 16; ++tl) {
;       float a0 = pass ? bias.y : bias.x;
; #pragma unroll
;       for (int k = 0; k < 31; ++k) a0 += w[k] * (pass ? bfhi(rowv[tl + k]) : bflo(rowv[tl + k]));
;       cs[tl * 520 + c0 + pass] = a0;
;     }
	v_pk_fma_f32 v[150:151], v[222:223], v[62:63], v[150:151]
	v_pk_fma_f32 v[148:149], v[222:223], v[60:61], v[148:149]
	v_pk_fma_f32 v[144:145], v[222:223], v[58:59], v[144:145]
	v_pk_fma_f32 v[140:141], v[222:223], v[124:125], v[140:141]
	v_pk_fma_f32 v[138:139], v[222:223], v[122:123], v[138:139]
	v_pk_fma_f32 v[136:137], v[222:223], v[132:133], v[136:137]
	v_pk_fma_f32 v[134:135], v[222:223], v[130:131], v[134:135]
	v_pk_fma_f32 v[100:101], v[222:223], v[128:129], v[100:101]
	v_pk_fma_f32 v[78:79], v[222:223], v[126:127], v[78:79]
	v_pk_fma_f32 v[48:49], v[222:223], v[120:121], v[48:49]
	v_pk_fma_f32 v[2:3], v[222:223], v[118:119], v[2:3]
	v_lshlrev_b32_e32 v114, 16, v159
	v_pk_fma_f32 v[166:167], v[224:225], v[66:67], v[166:167]
	v_pk_fma_f32 v[154:155], v[224:225], v[64:65], v[154:155]
	v_pk_fma_f32 v[152:153], v[224:225], v[62:63], v[152:153]
	v_pk_fma_f32 v[150:151], v[224:225], v[60:61], v[150:151]
	v_pk_fma_f32 v[148:149], v[224:225], v[58:59], v[148:149]
	v_pk_fma_f32 v[144:145], v[224:225], v[56:57], v[144:145]
	v_and_b32_e32 v115, 0xffff0000, v159
	v_pk_fma_f32 v[140:141], v[224:225], v[122:123], v[140:141]
	v_pk_fma_f32 v[138:139], v[224:225], v[132:133], v[138:139]
	v_pk_fma_f32 v[136:137], v[224:225], v[130:131], v[136:137]
	v_pk_fma_f32 v[134:135], v[224:225], v[128:129], v[134:135]
	v_pk_fma_f32 v[100:101], v[224:225], v[126:127], v[100:101]
	v_pk_fma_f32 v[78:79], v[224:225], v[120:121], v[78:79]
	v_pk_fma_f32 v[48:49], v[224:225], v[118:119], v[48:49]
	v_pk_fma_f32 v[2:3], v[224:225], v[116:117], v[2:3]
	v_lshlrev_b32_e32 v112, 16, v158
	v_pk_fma_f32 v[166:167], v[226:227], v[64:65], v[166:167]
	v_pk_fma_f32 v[154:155], v[226:227], v[62:63], v[154:155]
	v_pk_fma_f32 v[152:153], v[226:227], v[60:61], v[152:153]
	v_pk_fma_f32 v[150:151], v[226:227], v[58:59], v[150:151]
	v_pk_fma_f32 v[148:149], v[226:227], v[56:57], v[148:149]
	v_pk_fma_f32 v[144:145], v[226:227], v[54:55], v[144:145]
	v_pk_fma_f32 v[140:141], v[226:227], v[132:133], v[140:141]
	v_and_b32_e32 v113, 0xffff0000, v158
	v_pk_fma_f32 v[138:139], v[226:227], v[130:131], v[138:139]
	v_pk_fma_f32 v[136:137], v[226:227], v[128:129], v[136:137]
	v_pk_fma_f32 v[134:135], v[226:227], v[126:127], v[134:135]
	v_pk_fma_f32 v[100:101], v[226:227], v[120:121], v[100:101]
	v_pk_fma_f32 v[78:79], v[226:227], v[118:119], v[78:79]
	v_pk_fma_f32 v[48:49], v[226:227], v[116:117], v[48:49]
	v_pk_fma_f32 v[2:3], v[226:227], v[114:115], v[2:3]
	v_lshlrev_b32_e32 v110, 16, v111
	v_pk_fma_f32 v[166:167], v[228:229], v[62:63], v[166:167]
	v_pk_fma_f32 v[154:155], v[228:229], v[60:61], v[154:155]
	v_pk_fma_f32 v[152:153], v[228:229], v[58:59], v[152:153]
	v_pk_fma_f32 v[150:151], v[228:229], v[56:57], v[150:151]
	v_pk_fma_f32 v[148:149], v[228:229], v[54:55], v[148:149]
	v_pk_fma_f32 v[144:145], v[228:229], v[124:125], v[144:145]
	v_pk_fma_f32 v[140:141], v[228:229], v[130:131], v[140:141]
	v_pk_fma_f32 v[138:139], v[228:229], v[128:129], v[138:139]
	v_and_b32_e32 v111, 0xffff0000, v111
	v_pk_fma_f32 v[136:137], v[228:229], v[126:127], v[136:137]
	v_pk_fma_f32 v[134:135], v[228:229], v[120:121], v[134:135]
	v_pk_fma_f32 v[100:101], v[228:229], v[118:119], v[100:101]
	v_pk_fma_f32 v[78:79], v[228:229], v[116:117], v[78:79]
	v_pk_fma_f32 v[48:49], v[228:229], v[114:115], v[48:49]
	v_pk_fma_f32 v[2:3], v[228:229], v[112:113], v[2:3]
	v_lshlrev_b32_e32 v108, 16, v109
	v_pk_fma_f32 v[166:167], v[230:231], v[60:61], v[166:167]
	v_pk_fma_f32 v[154:155], v[230:231], v[58:59], v[154:155]
	v_pk_fma_f32 v[152:153], v[230:231], v[56:57], v[152:153]
	v_pk_fma_f32 v[150:151], v[230:231], v[54:55], v[150:151]
	v_pk_fma_f32 v[148:149], v[230:231], v[124:125], v[148:149]
	v_pk_fma_f32 v[144:145], v[230:231], v[122:123], v[144:145]
	v_pk_fma_f32 v[140:141], v[230:231], v[128:129], v[140:141]
	v_pk_fma_f32 v[138:139], v[230:231], v[126:127], v[138:139]
	v_pk_fma_f32 v[136:137], v[230:231], v[120:121], v[136:137]
	v_and_b32_e32 v109, 0xffff0000, v109
	v_pk_fma_f32 v[134:135], v[230:231], v[118:119], v[134:135]
	v_pk_fma_f32 v[100:101], v[230:231], v[116:117], v[100:101]
	v_pk_fma_f32 v[78:79], v[230:231], v[114:115], v[78:79]
	v_pk_fma_f32 v[48:49], v[230:231], v[112:113], v[48:49]
	v_pk_fma_f32 v[2:3], v[230:231], v[110:111], v[2:3]
	v_lshlrev_b32_e32 v106, 16, v107
	v_pk_fma_f32 v[166:167], v[232:233], v[58:59], v[166:167]
	v_pk_fma_f32 v[154:155], v[232:233], v[56:57], v[154:155]
	v_pk_fma_f32 v[152:153], v[232:233], v[54:55], v[152:153]
	v_pk_fma_f32 v[150:151], v[232:233], v[124:125], v[150:151]
	v_pk_fma_f32 v[148:149], v[232:233], v[122:123], v[148:149]
	v_pk_fma_f32 v[144:145], v[232:233], v[132:133], v[144:145]
	v_pk_fma_f32 v[140:141], v[232:233], v[126:127], v[140:141]
	v_pk_fma_f32 v[138:139], v[232:233], v[120:121], v[138:139]
	v_pk_fma_f32 v[136:137], v[232:233], v[118:119], v[136:137]
	v_pk_fma_f32 v[134:135], v[232:233], v[116:117], v[134:135]
	v_and_b32_e32 v107, 0xffff0000, v107
	v_pk_fma_f32 v[100:101], v[232:233], v[114:115], v[100:101]
	v_pk_fma_f32 v[78:79], v[232:233], v[112:113], v[78:79]
	v_pk_fma_f32 v[48:49], v[232:233], v[110:111], v[48:49]
	v_pk_fma_f32 v[2:3], v[232:233], v[108:109], v[2:3]
	v_lshlrev_b32_e32 v104, 16, v105
	v_pk_fma_f32 v[166:167], v[234:235], v[56:57], v[166:167]
	v_pk_fma_f32 v[154:155], v[234:235], v[54:55], v[154:155]
; DI int half_id() { return __builtin_amdgcn_readfirstlane((int)(threadIdx.x >> 8)); }
; DI void hsync() { hsync_impl(false); }
; DI float bflo(unsigned u) { return __uint_as_float(u << 16); }
; DI float bfhi(unsigned u) { return __uint_as_float(u & 0xffff0000u); }
; DI void hsync_impl(const bool INIT) {
;     ...
;   asm volatile("s_waitcnt vmcnt(0) lgkmcnt(0)" ::: "memory");
;   if ((threadIdx.x & 63) == 0) {
;     const int h2 = 2 * half_id();
;     const unsigned gen = __hip_atomic_load(&hb[h2 + 1], __ATOMIC_RELAXED, __HIP_MEMORY_SCOPE_WORKGROUP);
;     const unsigned old = __hip_atomic_fetch_add(&hb[h2], 1u, __ATOMIC_RELAXED, __HIP_MEMORY_SCOPE_WORKGROUP);
;     if (old == 3u) {
;       __hip_atomic_store(&hb[h2], 0u, __ATOMIC_RELAXED, __HIP_MEMORY_SCOPE_WORKGROUP);
;       asm volatile("s_waitcnt vmcnt(0) lgkmcnt(0)" ::: "memory");
;       __hip_atomic_fetch_add(&hb[h2 + 1], 1u, __ATOMIC_RELAXED, __HIP_MEMORY_SCOPE_WORKGROUP);
;     } else {
;       while (__hip_atomic_load(&hb[h2 + 1], __ATOMIC_RELAXED, __HIP_MEMORY_SCOPE_WORKGROUP) == gen) __builtin_amdgcn_s_sleep(1);
; DI void conv_item(const Params& p, int item, char* smem) {
;     ...
;   for (int pass = 0; pass < 2; ++pass) {
;     float w[31];
; #pragma unroll
;     for (int k = 0; k < 31; ++k) w[k] = p.w_dw[k * 512 + c0 + pass];
; #pragma unroll
;     for (int tl = 0; tl < 16; ++tl) {
;       float a0 = pass ? bias.y : bias.x;
; #pragma unroll
;       for (int k = 0; k < 31; ++k) a0 += w[k] * (pass ? bfhi(rowv[tl + k]) : bflo(rowv[tl + k]));
;       cs[tl * 520 + c0 + pass] = a0;
;     }
;   }
;   hsync();
	v_pk_fma_f32 v[152:153], v[234:235], v[124:125], v[152:153]
	v_pk_fma_f32 v[150:151], v[234:235], v[122:123], v[150:151]
	v_pk_fma_f32 v[148:149], v[234:235], v[132:133], v[148:149]
	v_pk_fma_f32 v[144:145], v[234:235], v[130:131], v[144:145]
	v_pk_fma_f32 v[140:141], v[234:235], v[120:121], v[140:141]
	v_pk_fma_f32 v[138:139], v[234:235], v[118:119], v[138:139]
	v_pk_fma_f32 v[136:137], v[234:235], v[116:117], v[136:137]
	v_pk_fma_f32 v[134:135], v[234:235], v[114:115], v[134:135]
	v_pk_fma_f32 v[100:101], v[234:235], v[112:113], v[100:101]
	v_and_b32_e32 v105, 0xffff0000, v105
	v_pk_fma_f32 v[78:79], v[234:235], v[110:111], v[78:79]
	v_pk_fma_f32 v[48:49], v[234:235], v[108:109], v[48:49]
	v_pk_fma_f32 v[2:3], v[234:235], v[106:107], v[2:3]
	v_lshlrev_b32_e32 v102, 16, v103
	v_pk_fma_f32 v[166:167], v[236:237], v[54:55], v[166:167]
	v_pk_fma_f32 v[154:155], v[236:237], v[124:125], v[154:155]
	v_pk_fma_f32 v[152:153], v[236:237], v[122:123], v[152:153]
	v_pk_fma_f32 v[150:151], v[236:237], v[132:133], v[150:151]
	v_pk_fma_f32 v[148:149], v[236:237], v[130:131], v[148:149]
	v_pk_fma_f32 v[144:145], v[236:237], v[128:129], v[144:145]
	v_pk_fma_f32 v[140:141], v[236:237], v[118:119], v[140:141]
	v_pk_fma_f32 v[138:139], v[236:237], v[116:117], v[138:139]
	v_pk_fma_f32 v[136:137], v[236:237], v[114:115], v[136:137]
	v_pk_fma_f32 v[134:135], v[236:237], v[112:113], v[134:135]
	v_pk_fma_f32 v[100:101], v[236:237], v[110:111], v[100:101]
	v_pk_fma_f32 v[78:79], v[236:237], v[108:109], v[78:79]
	v_and_b32_e32 v103, 0xffff0000, v103
	v_pk_fma_f32 v[48:49], v[236:237], v[106:107], v[48:49]
	v_pk_fma_f32 v[2:3], v[236:237], v[104:105], v[2:3]
	v_lshlrev_b32_e32 v4, 16, v157
	v_pk_fma_f32 v[166:167], v[238:239], v[124:125], v[166:167]
	v_pk_fma_f32 v[154:155], v[238:239], v[122:123], v[154:155]
	v_pk_fma_f32 v[152:153], v[238:239], v[132:133], v[152:153]
	v_pk_fma_f32 v[150:151], v[238:239], v[130:131], v[150:151]
	v_pk_fma_f32 v[148:149], v[238:239], v[128:129], v[148:149]
	v_pk_fma_f32 v[144:145], v[238:239], v[126:127], v[144:145]
	v_pk_fma_f32 v[140:141], v[238:239], v[116:117], v[140:141]
	v_pk_fma_f32 v[138:139], v[238:239], v[114:115], v[138:139]
	v_pk_fma_f32 v[136:137], v[238:239], v[112:113], v[136:137]
	v_pk_fma_f32 v[134:135], v[238:239], v[110:111], v[134:135]
	v_pk_fma_f32 v[100:101], v[238:239], v[108:109], v[100:101]
	v_pk_fma_f32 v[78:79], v[238:239], v[106:107], v[78:79]
	v_pk_fma_f32 v[48:49], v[238:239], v[104:105], v[48:49]
	v_and_b32_e32 v5, 0xffff0000, v157
	v_pk_fma_f32 v[2:3], v[238:239], v[102:103], v[2:3]
	v_pk_fma_f32 v[166:167], v[240:241], v[122:123], v[166:167]
	v_pk_fma_f32 v[154:155], v[240:241], v[132:133], v[154:155]
	v_pk_fma_f32 v[152:153], v[240:241], v[130:131], v[152:153]
	v_pk_fma_f32 v[150:151], v[240:241], v[128:129], v[150:151]
	v_pk_fma_f32 v[148:149], v[240:241], v[126:127], v[148:149]
	v_pk_fma_f32 v[144:145], v[240:241], v[120:121], v[144:145]
	v_pk_fma_f32 v[140:141], v[240:241], v[114:115], v[140:141]
	v_pk_fma_f32 v[138:139], v[240:241], v[112:113], v[138:139]
	v_pk_fma_f32 v[136:137], v[240:241], v[110:111], v[136:137]
	v_pk_fma_f32 v[134:135], v[240:241], v[108:109], v[134:135]
	v_pk_fma_f32 v[100:101], v[240:241], v[106:107], v[100:101]
	v_pk_fma_f32 v[78:79], v[240:241], v[104:105], v[78:79]
	v_pk_fma_f32 v[48:49], v[240:241], v[102:103], v[48:49]
	v_pk_fma_f32 v[2:3], v[240:241], v[4:5], v[2:3]
	ds_write_b64 v172, v[166:167]
	ds_write_b64 v172, v[154:155] offset:2080
	ds_write_b64 v172, v[152:153] offset:4160
	ds_write_b64 v172, v[150:151] offset:6240
	ds_write_b64 v172, v[148:149] offset:8320
	ds_write_b64 v172, v[144:145] offset:10400
	ds_write_b64 v172, v[140:141] offset:16640
	ds_write_b64 v172, v[138:139] offset:18720
	ds_write_b64 v172, v[136:137] offset:20800
	ds_write_b64 v172, v[134:135] offset:22880
	ds_write_b64 v172, v[100:101] offset:24960
	ds_write_b64 v172, v[78:79] offset:27040
	ds_write_b64 v172, v[48:49] offset:29120
	ds_write_b64 v172, v[2:3] offset:31200
	s_waitcnt vmcnt(0) lgkmcnt(0)
	v_readlane_b32 s37, v253, 17
	v_readlane_b32 s38, v253, 18
	v_readlane_b32 s39, v253, 19
	v_readlane_b32 s42, v253, 22
	v_readlane_b32 s43, v253, 23
	v_readlane_b32 s44, v253, 24
	v_readlane_b32 s45, v253, 25
	v_readlane_b32 s46, v253, 26
	v_readlane_b32 s47, v253, 27
	v_readlane_b32 s48, v253, 28
	v_readlane_b32 s49, v253, 29
	v_readlane_b32 s50, v253, 30
	v_readlane_b32 s51, v253, 31
	s_and_saveexec_b64 s[0:1], s[4:5]
	s_cbranch_execz .LBB0_743
	v_readfirstlane_b32 s13, v211
	s_lshr_b32 s13, s13, 5
	s_and_b32 s13, s13, 0x7fffff8
	v_mov_b32_e32 v2, s13
	ds_read_b32 v2, v2 offset:4
	s_mov_b64 s[14:15], exec
	v_mbcnt_lo_u32_b32 v3, s14, 0
	v_mbcnt_hi_u32_b32 v3, s15, v3
	v_cmp_eq_u32_e32 vcc, 0, v3
	s_and_saveexec_b64 s[16:17], vcc
	s_bcnt1_i32_b64 s14, s[14:15]
	v_mov_b32_e32 v4, s13
	v_mov_b32_e32 v5, s14
	ds_add_rtn_u32 v4, v4, v5
	s_or_b64 exec, exec, s[16:17]
	s_waitcnt lgkmcnt(0)
	v_readfirstlane_b32 s14, v4
	s_nop 1
	v_add_u32_e32 v3, s14, v3
	v_cmp_ne_u32_e32 vcc, 3, v3
	s_and_saveexec_b64 s[14:15], vcc
	s_xor_b64 s[14:15], exec, s[14:15]
	s_cbranch_execz .LBB0_740
	v_mov_b32_e32 v3, s13
	ds_read_b32 v3, v3 offset:4
	s_waitcnt lgkmcnt(0)
	v_cmp_ne_u32_e32 vcc, v3, v2
	s_cbranch_vccnz .LBB0_740
